# phase0 DFT tables: 2x2048 distinct twiddles computed once per workgroup into LDS by the original code, other chunks gather them (bit-identical)
# speedup vs baseline: 1.0080x; 1.0019x over previous
.LBB0_100:
	s_or_b64 exec, exec, s[0:1]
	s_lshl_b32 s9, s60, 12
	s_movk_i32 s10, 0x3fff
	s_movk_i32 s11, 0xff80
	s_mov_b32 s18, 0x7f800000
	v_mov_b32_e32 v7, 0xbf1f24be
	v_mov_b32_e32 v8, 0x3e642e9d
	s_movk_i32 s19, 0x1f8
	s_mov_b32 s20, 0x103fff
	v_mov_b32_e32 v9, 0xfffe0000
	v_mov_b32_e32 v11, 0x7fc00000
	v_mov_b32_e32 v182, v1
	s_cmp_lt_u32 s60, 32
	s_cbranch_scc1 .Ldft_orig
	s_mov_b32 s100, 0
	s_mov_b64 s[4:5], 0
	s_mov_b64 s[2:3], exec
	v_and_b32_e32 v1, 0xff, v82
	v_mov_b32_e32 v2, 0x4100
	v_mov_b32_e32 v3, 0xc100
	v_cmp_lt_u32_e32 vcc, 0xff, v82
	s_nop 1
	v_cndmask_b32_e32 v2, v2, v3, vcc
	v_add_u32_e32 v1, v1, v2
	v_mov_b32_e32 v6, 0
	s_branch .LBB0_103
.Ldft_orig:
	s_mov_b32 s100, 2
	s_mov_b32 s0, 0x104000
	v_cmp_gt_i32_e32 vcc, s0, v1
	s_and_saveexec_b64 s[2:3], vcc
	s_cbranch_execz .LBB0_137
	v_lshl_add_u32 v6, s62, 12, v4
	s_mov_b64 s[4:5], 0
	s_branch .LBB0_103
.Ldft_lutdone:
	v_lshlrev_b32_e32 v2, 4, v82
	v_add_u32_e32 v2, 0x20000, v2
	ds_write_b128 v2, v[12:15]
	s_waitcnt lgkmcnt(0)
	s_barrier
	s_mov_b32 s100, 1
	v_mov_b32_e32 v1, v182
	s_mov_b64 s[4:5], 0
	s_mov_b32 s0, 0x104000
	v_cmp_gt_i32_e32 vcc, s0, v1
	s_and_saveexec_b64 s[2:3], vcc
	s_cbranch_execz .LBB0_137
	v_lshlrev_b32_e32 v6, 3, v82
	v_lshl_add_u32 v6, s62, 12, v6
	s_cmp_lt_u32 s62, 32
	s_cbranch_scc1 .LBB0_103
.Ldft_gather:
	s_add_u32 s0, s14, 0x8d00000
	s_addc_u32 s1, s15, 0
	s_movk_i32 s6, 0xffe
.Ldft_gloop:
	v_add_u32_e32 v2, 0xffffc000, v1
	v_lshrrev_b32_e32 v3, 8, v2
	v_and_b32_e32 v4, 0xff, v2
	v_lshlrev_b32_e32 v4, 3, v4
	v_lshrrev_b32_e32 v5, 8, v3
	v_and_b32_e32 v13, 0x7f, v3
	v_lshl_add_u32 v5, v5, 7, v13
	v_bfe_u32 v13, v3, 7, 1
	v_lshlrev_b32_e32 v13, 12, v13
	v_add_u32_e32 v13, 0x20000, v13
	v_mul_lo_u32 v14, v5, v4
	v_lshlrev_b32_e32 v14, 1, v14
	v_lshlrev_b32_e32 v5, 1, v5
	v_and_or_b32 v16, v14, s6, v13
	ds_read_u16 v18, v16
	v_add_u32_e32 v14, v14, v5
	v_and_or_b32 v16, v14, s6, v13
	ds_read_u16 v19, v16
	v_add_u32_e32 v14, v14, v5
	v_and_or_b32 v16, v14, s6, v13
	ds_read_u16 v20, v16
	v_add_u32_e32 v14, v14, v5
	v_and_or_b32 v16, v14, s6, v13
	ds_read_u16 v21, v16
	v_add_u32_e32 v14, v14, v5
	v_and_or_b32 v16, v14, s6, v13
	ds_read_u16 v22, v16
	v_add_u32_e32 v14, v14, v5
	v_and_or_b32 v16, v14, s6, v13
	ds_read_u16 v23, v16
	v_add_u32_e32 v14, v14, v5
	v_and_or_b32 v16, v14, s6, v13
	ds_read_u16 v24, v16
	v_add_u32_e32 v14, v14, v5
	v_and_or_b32 v16, v14, s6, v13
	ds_read_u16 v25, v16
	v_lshlrev_b32_e32 v17, 4, v2
	v_add_u32_e32 v1, s8, v1
	v_cmp_lt_i32_e32 vcc, s20, v1
	s_waitcnt lgkmcnt(0)
	v_lshl_or_b32 v18, v19, 16, v18
	v_lshl_or_b32 v19, v21, 16, v20
	v_lshl_or_b32 v20, v23, 16, v22
	v_lshl_or_b32 v21, v25, 16, v24
	global_store_dwordx4 v17, v[18:21], s[0:1]
	s_andn2_b64 exec, exec, vcc
	s_cbranch_execnz .Ldft_gloop
	s_branch .LBB0_137
.LBB0_102:
	s_or_b64 exec, exec, s[0:1]
	v_cmp_class_f32_e64 vcc, v28, s19
	v_add_u32_e32 v1, s8, v1
	v_lshl_add_u64 v[4:5], s[14:15], 0, v[4:5]
	v_cndmask_b32_e32 v17, v11, v29, vcc
	v_cmp_class_f32_e64 vcc, v26, s19
	v_lshl_add_u64 v[2:3], v[2:3], 1, v[4:5]
	v_add_u32_e32 v6, s9, v6
	v_cndmask_b32_e32 v26, v11, v27, vcc
	v_cmp_class_f32_e64 vcc, v24, s19
	v_mul_f32_e32 v17, v12, v17
	v_mul_f32_e32 v26, v12, v26
	v_cndmask_b32_e32 v24, v11, v25, vcc
	v_cmp_class_f32_e64 vcc, v22, s19
	v_mul_f32_e32 v24, v12, v24
	s_nop 0
	v_cndmask_b32_e32 v22, v11, v23, vcc
	v_cmp_class_f32_e64 vcc, v20, s19
	v_mul_f32_e32 v22, v12, v22
	s_nop 0
	v_cndmask_b32_e32 v20, v11, v21, vcc
	v_cmp_class_f32_e64 vcc, v18, s19
	v_mul_f32_e32 v20, v12, v20
	s_nop 0
	v_cndmask_b32_e32 v18, v11, v19, vcc
	v_cmp_class_f32_e64 vcc, v13, s19
	v_mul_f32_e32 v18, v12, v18
	s_nop 0
	v_cndmask_b32_e32 v13, v11, v14, vcc
	v_cmp_class_f32_e64 vcc, v15, s19
	v_mul_f32_e32 v13, v12, v13
	s_nop 0
	v_cndmask_b32_e32 v14, v11, v16, vcc
	v_cmp_lt_i32_e32 vcc, s20, v1
	v_mul_f32_e32 v15, v12, v14
	s_or_b64 s[4:5], vcc, s[4:5]
	v_cvt_pk_bf16_f32 v12, v13, v18
	v_cvt_pk_bf16_f32 v13, v20, v22
	v_cvt_pk_bf16_f32 v14, v24, v26
	v_cvt_pk_bf16_f32 v15, v17, v15
	s_cmp_eq_u32 s100, 0
	s_cbranch_scc1 .Ldft_lutdone
	global_store_dwordx4 v[2:3], v[12:15], off
	s_andn2_b64 exec, exec, s[4:5]
	s_cbranch_execz .LBB0_137
	s_cmp_eq_u32 s100, 2
	s_cbranch_scc0 .Ldft_gather
